# small (64-row) GEMM tails: register prefetch distance 4 K-steps instead of 2 (P3, P9, P12 ctx tails)
# speedup vs baseline: 1.0048x; 1.0044x over previous
.LBB0_546:
	s_andn2_b64 vcc, exec, s[18:19]
	s_mov_b32 s25, s54
	s_mov_b32 s4, s31
	s_cbranch_vccnz .LBB0_539
	s_lshl_b32 s19, s21, 6
	s_addk_i32 s19, 0x4000
	s_lshl_b32 s18, s23, 7
	v_add_u32_e32 v26, s19, v46
	s_movk_i32 s2, 0x1600
	v_mad_i64_i32 v[38:39], s[50:51], v26, s2, v[32:33]
	v_add_u32_e32 v27, s18, v46
	v_mad_i64_i32 v[40:41], s[50:51], v27, s2, v[34:35]
	global_load_dwordx4 v[2:5], v[38:39], off
	global_load_dwordx4 v[6:9], v[40:41], off
	v_add_co_u32_e32 v22, vcc, 0x58000, v40
	v_add_u32_e32 v0, v30, v31
	s_nop 0
	v_addc_co_u32_e32 v23, vcc, 0, v41, vcc
	global_load_dwordx4 v[10:13], v[22:23], off
	global_load_dwordx4 v[122:125], v[38:39], off offset:128
	global_load_dwordx4 v[126:129], v[40:41], off offset:128
	s_nop 0
	global_load_dwordx4 v[130:133], v[22:23], off offset:128
	global_load_dwordx4 v[134:137], v[38:39], off offset:256
	global_load_dwordx4 v[138:141], v[40:41], off offset:256
	global_load_dwordx4 v[142:145], v[22:23], off offset:256
	global_load_dwordx4 v[146:149], v[38:39], off offset:384
	global_load_dwordx4 v[150:153], v[40:41], off offset:384
	global_load_dwordx4 v[154:157], v[22:23], off offset:384
	s_waitcnt lgkmcnt(0)
	s_barrier
	s_mov_b32 s25, 2
	s_waitcnt vmcnt(11)
	ds_write_b128 v0, v[2:5]
	s_waitcnt vmcnt(10)
	ds_write_b128 v0, v[6:9] offset:36864
	s_waitcnt vmcnt(9)
	ds_write_b128 v0, v[10:13] offset:46080
	v_mov_b64_e32 v[2:3], s[14:15]
	v_mad_i64_i32 v[44:45], s[50:51], v26, s2, v[2:3]
	v_mov_b32_e32 v26, 0
	v_mad_i64_i32 v[42:43], s[50:51], v27, s2, v[2:3]
	v_mov_b32_e32 v27, v26
	v_mov_b32_e32 v28, v26
	v_mov_b32_e32 v29, v26
	v_mov_b32_e32 v10, v26
	v_mov_b32_e32 v11, v26
	v_mov_b32_e32 v12, v26
	v_mov_b32_e32 v13, v26
	v_mov_b32_e32 v6, v26
	v_mov_b32_e32 v7, v26
	v_mov_b32_e32 v8, v26
	v_mov_b32_e32 v9, v26
	v_mov_b32_e32 v2, v26
	v_mov_b32_e32 v3, v26
	v_mov_b32_e32 v4, v26
	v_mov_b32_e32 v5, v26
	s_mov_b64 s[2:3], 0x200
	s_waitcnt lgkmcnt(0)
	s_barrier
.LBB0_548:
	s_add_i32 s4, s25, 2
	s_min_u32 s4, s4, 43
	s_lshl_b32 s4, s4, 7
	v_lshl_add_u64 v[110:111], v[38:39], 0, s[4:5]
	v_lshl_add_u64 v[118:119], v[40:41], 0, s[4:5]
	global_load_dwordx4 v[110:113], v[110:111], off
	global_load_dwordx4 v[114:117], v[118:119], off
	v_add_co_u32_e32 v118, vcc, s92, v118
	s_nop 1
	v_addc_co_u32_e32 v119, vcc, 0, v119, vcc
	global_load_dwordx4 v[118:121], v[118:119], off
	v_add_u32_e32 v59, v49, v51
	ds_read_b128 v[72:75], v52
	ds_read_b128 v[76:79], v59 offset:36864
	ds_read_b128 v[80:83], v59 offset:39168
	ds_read_b128 v[84:87], v59 offset:41472
	ds_read_b128 v[88:91], v59 offset:43776
	s_waitcnt lgkmcnt(3)
	v_mfma_f32_16x16x32_bf16 v[26:29], v[76:79], v[72:75], v[26:29]
	s_waitcnt lgkmcnt(2)
	v_mfma_f32_16x16x32_bf16 v[10:13], v[80:83], v[72:75], v[10:13]
	ds_read_b128 v[76:79], v52 offset:64
	ds_read_b128 v[80:83], v59 offset:36928
	s_waitcnt lgkmcnt(3)
	v_mfma_f32_16x16x32_bf16 v[6:9], v[84:87], v[72:75], v[6:9]
	ds_read_b128 v[84:87], v59 offset:39232
	ds_read_b128 v[92:95], v59 offset:41536
	ds_read_b128 v[96:99], v59 offset:43840
	s_waitcnt lgkmcnt(5)
	v_mfma_f32_16x16x32_bf16 v[2:5], v[88:91], v[72:75], v[2:5]
	s_waitcnt vmcnt(11)
	ds_write_b128 v0, v[122:125] offset:55296
	s_waitcnt vmcnt(10)
	ds_write_b128 v53, v[126:129]
	s_waitcnt vmcnt(9)
	ds_write_b128 v53, v[130:133] offset:9216
	s_waitcnt lgkmcnt(6)
	v_mfma_f32_16x16x32_bf16 v[14:17], v[80:83], v[76:79], v[26:29]
	s_waitcnt lgkmcnt(5)
	v_mfma_f32_16x16x32_bf16 v[10:13], v[84:87], v[76:79], v[10:13]
	s_waitcnt lgkmcnt(4)
	v_mfma_f32_16x16x32_bf16 v[6:9], v[92:95], v[76:79], v[6:9]
	s_waitcnt lgkmcnt(3)
	v_mfma_f32_16x16x32_bf16 v[2:5], v[96:99], v[76:79], v[2:5]
	s_waitcnt lgkmcnt(0)
	s_barrier
	s_add_i32 s4, s25, 3
	s_min_u32 s4, s4, 43
	s_lshl_b32 s4, s4, 7
	v_lshl_add_u64 v[122:123], v[38:39], 0, s[4:5]
	v_lshl_add_u64 v[130:131], v[40:41], 0, s[4:5]
	global_load_dwordx4 v[122:125], v[122:123], off
	global_load_dwordx4 v[126:129], v[130:131], off
	v_add_co_u32_e32 v130, vcc, s92, v130
	s_nop 1
	v_addc_co_u32_e32 v131, vcc, 0, v131, vcc
	global_load_dwordx4 v[130:133], v[130:131], off
	ds_read_b128 v[72:75], v52 offset:55296
	ds_read_b128 v[76:79], v54
	ds_read_b128 v[80:83], v54 offset:2304
	ds_read_b128 v[84:87], v54 offset:4608
	ds_read_b128 v[88:91], v54 offset:6912
	s_waitcnt lgkmcnt(3)
	v_mfma_f32_16x16x32_bf16 v[14:17], v[76:79], v[72:75], v[14:17]
	s_waitcnt lgkmcnt(2)
	v_mfma_f32_16x16x32_bf16 v[10:13], v[80:83], v[72:75], v[10:13]
	ds_read_b128 v[76:79], v52 offset:55360
	ds_read_b128 v[80:83], v55 offset:64
	s_waitcnt lgkmcnt(3)
	v_mfma_f32_16x16x32_bf16 v[6:9], v[84:87], v[72:75], v[6:9]
	ds_read_b128 v[84:87], v56 offset:64
	ds_read_b128 v[92:95], v57 offset:64
	ds_read_b128 v[96:99], v58 offset:64
	s_waitcnt lgkmcnt(5)
	v_mfma_f32_16x16x32_bf16 v[2:5], v[88:91], v[72:75], v[2:5]
	s_waitcnt lgkmcnt(3)
	v_mfma_f32_16x16x32_bf16 v[14:17], v[80:83], v[76:79], v[14:17]
	s_waitcnt vmcnt(11)
	ds_write_b128 v0, v[134:137]
	s_waitcnt vmcnt(10)
	ds_write_b128 v0, v[138:141] offset:36864
	s_waitcnt vmcnt(9)
	ds_write_b128 v0, v[142:145] offset:46080
	s_waitcnt lgkmcnt(5)
	v_mfma_f32_16x16x32_bf16 v[10:13], v[84:87], v[76:79], v[10:13]
	s_waitcnt lgkmcnt(4)
	v_mfma_f32_16x16x32_bf16 v[6:9], v[92:95], v[76:79], v[6:9]
	s_waitcnt lgkmcnt(3)
	v_mfma_f32_16x16x32_bf16 v[2:5], v[96:99], v[76:79], v[2:5]
	s_waitcnt lgkmcnt(0)
	s_barrier
	s_add_i32 s4, s25, 4
	s_min_u32 s4, s4, 43
	s_lshl_b32 s4, s4, 7
	v_lshl_add_u64 v[134:135], v[38:39], 0, s[4:5]
	v_lshl_add_u64 v[142:143], v[40:41], 0, s[4:5]
	global_load_dwordx4 v[134:137], v[134:135], off
	global_load_dwordx4 v[138:141], v[142:143], off
	v_add_co_u32_e32 v142, vcc, s92, v142
	s_nop 1
	v_addc_co_u32_e32 v143, vcc, 0, v143, vcc
	global_load_dwordx4 v[142:145], v[142:143], off
	ds_read_b128 v[72:75], v52
	ds_read_b128 v[76:79], v59 offset:36864
	ds_read_b128 v[80:83], v59 offset:39168
	ds_read_b128 v[84:87], v59 offset:41472
	ds_read_b128 v[88:91], v59 offset:43776
	s_waitcnt lgkmcnt(3)
	v_mfma_f32_16x16x32_bf16 v[14:17], v[76:79], v[72:75], v[14:17]
	s_waitcnt lgkmcnt(2)
	v_mfma_f32_16x16x32_bf16 v[10:13], v[80:83], v[72:75], v[10:13]
	ds_read_b128 v[76:79], v52 offset:64
	ds_read_b128 v[80:83], v59 offset:36928
	s_waitcnt lgkmcnt(3)
	v_mfma_f32_16x16x32_bf16 v[6:9], v[84:87], v[72:75], v[6:9]
	ds_read_b128 v[84:87], v59 offset:39232
	ds_read_b128 v[92:95], v59 offset:41536
	ds_read_b128 v[96:99], v59 offset:43840
	s_waitcnt lgkmcnt(5)
	v_mfma_f32_16x16x32_bf16 v[2:5], v[88:91], v[72:75], v[2:5]
	s_waitcnt vmcnt(11)
	ds_write_b128 v0, v[146:149] offset:55296
	s_waitcnt vmcnt(10)
	ds_write_b128 v53, v[150:153]
	s_waitcnt vmcnt(9)
	ds_write_b128 v53, v[154:157] offset:9216
	s_waitcnt lgkmcnt(6)
	v_mfma_f32_16x16x32_bf16 v[26:29], v[80:83], v[76:79], v[14:17]
	s_waitcnt lgkmcnt(5)
	v_mfma_f32_16x16x32_bf16 v[10:13], v[84:87], v[76:79], v[10:13]
	s_waitcnt lgkmcnt(4)
	v_mfma_f32_16x16x32_bf16 v[6:9], v[92:95], v[76:79], v[6:9]
	s_waitcnt lgkmcnt(3)
	v_mfma_f32_16x16x32_bf16 v[2:5], v[96:99], v[76:79], v[2:5]
	s_waitcnt lgkmcnt(0)
	s_barrier
	s_add_i32 s4, s25, 5
	s_min_u32 s4, s4, 43
	s_lshl_b32 s4, s4, 7
	v_lshl_add_u64 v[146:147], v[38:39], 0, s[4:5]
	v_lshl_add_u64 v[154:155], v[40:41], 0, s[4:5]
	global_load_dwordx4 v[146:149], v[146:147], off
	global_load_dwordx4 v[150:153], v[154:155], off
	v_add_co_u32_e32 v154, vcc, s92, v154
	s_nop 1
	v_addc_co_u32_e32 v155, vcc, 0, v155, vcc
	global_load_dwordx4 v[154:157], v[154:155], off
	ds_read_b128 v[72:75], v52 offset:55296
	ds_read_b128 v[76:79], v54
	ds_read_b128 v[80:83], v54 offset:2304
	ds_read_b128 v[84:87], v54 offset:4608
	ds_read_b128 v[88:91], v54 offset:6912
	s_waitcnt lgkmcnt(3)
	v_mfma_f32_16x16x32_bf16 v[26:29], v[76:79], v[72:75], v[26:29]
	s_waitcnt lgkmcnt(2)
	v_mfma_f32_16x16x32_bf16 v[10:13], v[80:83], v[72:75], v[10:13]
	ds_read_b128 v[76:79], v52 offset:55360
	ds_read_b128 v[80:83], v55 offset:64
	s_waitcnt lgkmcnt(3)
	v_mfma_f32_16x16x32_bf16 v[6:9], v[84:87], v[72:75], v[6:9]
	ds_read_b128 v[84:87], v56 offset:64
	ds_read_b128 v[92:95], v57 offset:64
	ds_read_b128 v[96:99], v58 offset:64
	s_waitcnt lgkmcnt(5)
	v_mfma_f32_16x16x32_bf16 v[2:5], v[88:91], v[72:75], v[2:5]
	s_waitcnt lgkmcnt(3)
	v_mfma_f32_16x16x32_bf16 v[26:29], v[80:83], v[76:79], v[26:29]
	s_waitcnt vmcnt(11)
	ds_write_b128 v0, v[110:113]
	s_waitcnt vmcnt(10)
	ds_write_b128 v0, v[114:117] offset:36864
	s_waitcnt vmcnt(9)
	ds_write_b128 v0, v[118:121] offset:46080
	s_waitcnt lgkmcnt(5)
	v_mfma_f32_16x16x32_bf16 v[10:13], v[84:87], v[76:79], v[10:13]
	s_waitcnt lgkmcnt(4)
	v_mfma_f32_16x16x32_bf16 v[6:9], v[92:95], v[76:79], v[6:9]
	s_waitcnt lgkmcnt(3)
	v_mfma_f32_16x16x32_bf16 v[2:5], v[96:99], v[76:79], v[2:5]
	s_waitcnt lgkmcnt(0)
	s_barrier
	s_add_i32 s4, s25, 4
	v_lshl_add_u64 v[42:43], v[42:43], 0, s[2:3]
	v_lshl_add_u64 v[44:45], v[44:45], 0, s[2:3]
	s_cmp_gt_u32 s25, 41
	s_mov_b32 s25, s4
	s_cbranch_scc0 .LBB0_548
	v_add_u32_e32 v0, s19, v48
	s_waitcnt vmcnt(2)
	v_or_b32_e32 v14, v0, v47
	v_cmp_lt_i32_e32 vcc, s97, v14
	v_ashrrev_i32_e32 v0, 11, v0
	v_ashrrev_i32_e32 v15, 31, v14
	s_waitcnt vmcnt(0)
	v_cndmask_b32_e64 v22, v0, 8, vcc
	v_add_u32_e32 v0, 0xffffc000, v14
	v_lshlrev_b64 v[16:17], 12, v[14:15]
	v_lshlrev_b64 v[14:15], 12, v[0:1]
	v_or_b32_e32 v24, s18, v50
	v_lshl_add_u64 v[18:19], s[44:45], 0, v[16:17]
	v_lshl_add_u64 v[20:21], s[46:47], 0, v[14:15]
	v_lshl_add_u64 v[16:17], s[48:49], 0, v[16:17]
	v_lshl_add_u64 v[14:15], s[16:17], 0, v[14:15]
	v_mul_hi_i32_i24_e32 v23, 0x9000, v22
	v_mul_i32_i24_e32 v22, 0x9000, v22
	v_ashrrev_i32_e32 v25, 31, v24
	v_lshl_add_u64 v[22:23], s[12:13], 0, v[22:23]
	v_cndmask_b32_e32 v15, v17, v15, vcc
	v_cndmask_b32_e32 v14, v16, v14, vcc
	v_lshlrev_b64 v[16:17], 2, v[24:25]
	s_waitcnt vmcnt(0)
	v_cndmask_b32_e32 v19, v19, v21, vcc
	v_cndmask_b32_e32 v18, v18, v20, vcc
	v_lshl_add_u64 v[22:23], v[22:23], 0, v[16:17]
	v_lshl_add_u64 v[24:25], v[18:19], 0, v[16:17]
	v_lshl_add_u64 v[38:39], v[14:15], 0, v[16:17]
	global_load_dwordx4 v[14:17], v[22:23], off
	global_load_dwordx4 v[18:21], v[24:25], off
	s_waitcnt vmcnt(1)
	v_pk_mul_f32 v[14:15], v[14:15], 0.5 op_sel_hi:[1,0]
	v_pk_mul_f32 v[16:17], v[16:17], 0.5 op_sel_hi:[1,0]
	s_waitcnt vmcnt(0)
	v_pk_fma_f32 v[14:15], v[26:27], v[14:15], v[18:19]
	v_pk_fma_f32 v[16:17], v[28:29], v[16:17], v[20:21]
	global_store_dwordx4 v[38:39], v[14:17], off
	global_load_dwordx4 v[14:17], v[22:23], off offset:64
	s_nop 0
	global_load_dwordx4 v[18:21], v[24:25], off offset:64
	s_waitcnt vmcnt(1)
	v_pk_mul_f32 v[14:15], v[14:15], 0.5 op_sel_hi:[1,0]
	s_waitcnt vmcnt(0)
	v_pk_fma_f32 v[10:11], v[10:11], v[14:15], v[18:19]
	v_pk_mul_f32 v[14:15], v[16:17], 0.5 op_sel_hi:[1,0]
	s_nop 0
	v_pk_fma_f32 v[12:13], v[12:13], v[14:15], v[20:21]
	global_store_dwordx4 v[38:39], v[10:13], off offset:64
	global_load_dwordx4 v[10:13], v[22:23], off offset:128
	s_nop 0
	global_load_dwordx4 v[14:17], v[24:25], off offset:128
	s_waitcnt vmcnt(1)
	v_pk_mul_f32 v[10:11], v[10:11], 0.5 op_sel_hi:[1,0]
	s_waitcnt vmcnt(0)
	v_pk_fma_f32 v[6:7], v[6:7], v[10:11], v[14:15]
	v_pk_mul_f32 v[10:11], v[12:13], 0.5 op_sel_hi:[1,0]
	s_nop 0
	v_pk_fma_f32 v[8:9], v[8:9], v[10:11], v[16:17]
	global_store_dwordx4 v[38:39], v[6:9], off offset:128
	global_load_dwordx4 v[6:9], v[22:23], off offset:192
	s_nop 0
	global_load_dwordx4 v[10:13], v[24:25], off offset:192
	s_waitcnt vmcnt(1)
	v_pk_mul_f32 v[6:7], v[6:7], 0.5 op_sel_hi:[1,0]
	s_waitcnt vmcnt(0)
	v_pk_fma_f32 v[2:3], v[2:3], v[6:7], v[10:11]
	v_pk_mul_f32 v[6:7], v[8:9], 0.5 op_sel_hi:[1,0]
	s_nop 0
	v_pk_fma_f32 v[4:5], v[4:5], v[6:7], v[12:13]
	global_store_dwordx4 v[38:39], v[2:5], off offset:192
	s_mov_b32 s26, 0
	s_mov_b32 s25, s21
	s_mov_b32 s4, s23
	s_branch .LBB0_539

.LBB0_1321:
	s_andn2_b64 vcc, exec, s[16:17]
	s_mov_b32 s26, s51
	s_mov_b32 s4, s50
	s_cbranch_vccnz .LBB0_1314
	s_lshl_b32 s17, s23, 6
	s_addk_i32 s17, 0x4000
	v_add_u32_e32 v2, s17, v46
	s_lshl_b32 s16, s25, 7
	v_ashrrev_i32_e32 v3, 31, v2
	v_lshlrev_b64 v[26:27], 11, v[2:3]
	v_add_u32_e32 v2, s16, v46
	v_ashrrev_i32_e32 v3, 31, v2
	v_lshl_add_u64 v[38:39], v[32:33], 0, v[26:27]
	v_lshlrev_b64 v[28:29], 11, v[2:3]
	v_lshl_add_u64 v[40:41], v[34:35], 0, v[28:29]
	global_load_dwordx4 v[2:5], v[38:39], off
	global_load_dwordx4 v[18:21], v[40:41], off
	v_add_co_u32_e32 v14, vcc, 0x20000, v40
	v_add_u32_e32 v0, v30, v31
	s_nop 0
	v_addc_co_u32_e32 v15, vcc, 0, v41, vcc
	global_load_dwordx4 v[22:25], v[14:15], off
	global_load_dwordx4 v[122:125], v[38:39], off offset:128
	global_load_dwordx4 v[126:129], v[40:41], off offset:128
	s_nop 0
	global_load_dwordx4 v[130:133], v[14:15], off offset:128
	global_load_dwordx4 v[134:137], v[38:39], off offset:256
	global_load_dwordx4 v[138:141], v[40:41], off offset:256
	global_load_dwordx4 v[142:145], v[14:15], off offset:256
	global_load_dwordx4 v[146:149], v[38:39], off offset:384
	global_load_dwordx4 v[150:153], v[40:41], off offset:384
	global_load_dwordx4 v[154:157], v[14:15], off offset:384
	v_lshl_add_u64 v[44:45], s[46:47], 0, v[26:27]
	v_mov_b32_e32 v26, 0
	s_barrier
	v_lshl_add_u64 v[42:43], s[46:47], 0, v[28:29]
	s_mov_b32 s26, 2
	v_mov_b32_e32 v27, v26
	v_mov_b32_e32 v28, v26
	v_mov_b32_e32 v29, v26
	s_mov_b64 s[48:49], 0x200
	s_mov_b32 s3, 0x3200000
	s_waitcnt vmcnt(11)
	ds_write_b128 v0, v[2:5]
	s_waitcnt vmcnt(10)
	ds_write_b128 v0, v[18:21] offset:36864
	s_waitcnt vmcnt(9)
	ds_write_b128 v0, v[22:25] offset:46080
	v_mov_b32_e32 v22, v26
	v_mov_b32_e32 v23, v26
	v_mov_b32_e32 v24, v26
	v_mov_b32_e32 v25, v26
	v_mov_b32_e32 v18, v26
	v_mov_b32_e32 v19, v26
	v_mov_b32_e32 v20, v26
	v_mov_b32_e32 v21, v26
	v_mov_b32_e32 v2, v26
	v_mov_b32_e32 v3, v26
	v_mov_b32_e32 v4, v26
	v_mov_b32_e32 v5, v26
	s_waitcnt lgkmcnt(0)
	s_barrier
.LBB0_1323:
	s_add_i32 s4, s26, 2
	s_min_u32 s4, s4, 15
	s_lshl_b32 s4, s4, 7
	v_lshl_add_u64 v[110:111], v[38:39], 0, s[4:5]
	v_lshl_add_u64 v[118:119], v[40:41], 0, s[4:5]
	global_load_dwordx4 v[110:113], v[110:111], off
	global_load_dwordx4 v[114:117], v[118:119], off
	v_add_co_u32_e32 v118, vcc, s34, v118
	s_nop 1
	v_addc_co_u32_e32 v119, vcc, 0, v119, vcc
	global_load_dwordx4 v[118:121], v[118:119], off
	s_mov_b32 s2, 0x2800000
	s_mov_b32 s2, 0x2820000
	s_nop 0
	v_add_u32_e32 v59, v49, v51
	ds_read_b128 v[72:75], v52
	ds_read_b128 v[76:79], v59 offset:36864
	ds_read_b128 v[80:83], v59 offset:39168
	ds_read_b128 v[84:87], v59 offset:41472
	ds_read_b128 v[88:91], v59 offset:43776
	s_waitcnt lgkmcnt(3)
	v_mfma_f32_16x16x32_bf16 v[26:29], v[76:79], v[72:75], v[26:29]
	s_waitcnt lgkmcnt(2)
	v_mfma_f32_16x16x32_bf16 v[22:25], v[80:83], v[72:75], v[22:25]
	ds_read_b128 v[76:79], v52 offset:64
	ds_read_b128 v[80:83], v59 offset:36928
	s_waitcnt lgkmcnt(3)
	v_mfma_f32_16x16x32_bf16 v[18:21], v[84:87], v[72:75], v[18:21]
	ds_read_b128 v[84:87], v59 offset:39232
	ds_read_b128 v[92:95], v59 offset:41536
	ds_read_b128 v[96:99], v59 offset:43840
	s_waitcnt lgkmcnt(5)
	v_mfma_f32_16x16x32_bf16 v[2:5], v[88:91], v[72:75], v[2:5]
	s_waitcnt vmcnt(11)
	ds_write_b128 v0, v[122:125] offset:55296
	s_waitcnt vmcnt(10)
	ds_write_b128 v53, v[126:129]
	s_waitcnt vmcnt(9)
	ds_write_b128 v53, v[130:133] offset:9216
	s_waitcnt lgkmcnt(6)
	v_mfma_f32_16x16x32_bf16 v[6:9], v[80:83], v[76:79], v[26:29]
	s_waitcnt lgkmcnt(5)
	v_mfma_f32_16x16x32_bf16 v[10:13], v[84:87], v[76:79], v[22:25]
	s_waitcnt lgkmcnt(4)
	v_mfma_f32_16x16x32_bf16 v[14:17], v[92:95], v[76:79], v[18:21]
	s_waitcnt lgkmcnt(3)
	v_mfma_f32_16x16x32_bf16 v[2:5], v[96:99], v[76:79], v[2:5]
	s_waitcnt lgkmcnt(0)
	s_barrier
	s_add_i32 s4, s26, 3
	s_min_u32 s4, s4, 15
	s_lshl_b32 s4, s4, 7
	v_lshl_add_u64 v[122:123], v[38:39], 0, s[4:5]
	v_lshl_add_u64 v[130:131], v[40:41], 0, s[4:5]
	global_load_dwordx4 v[122:125], v[122:123], off
	global_load_dwordx4 v[126:129], v[130:131], off
	v_add_co_u32_e32 v130, vcc, s34, v130
	s_nop 1
	v_addc_co_u32_e32 v131, vcc, 0, v131, vcc
	global_load_dwordx4 v[130:133], v[130:131], off
	s_nop 0
	ds_read_b128 v[72:75], v52 offset:55296
	ds_read_b128 v[76:79], v54
	ds_read_b128 v[80:83], v54 offset:2304
	ds_read_b128 v[84:87], v54 offset:4608
	ds_read_b128 v[88:91], v54 offset:6912
	s_waitcnt lgkmcnt(3)
	v_mfma_f32_16x16x32_bf16 v[6:9], v[76:79], v[72:75], v[6:9]
	s_waitcnt lgkmcnt(2)
	v_mfma_f32_16x16x32_bf16 v[10:13], v[80:83], v[72:75], v[10:13]
	ds_read_b128 v[76:79], v52 offset:55360
	ds_read_b128 v[80:83], v55 offset:64
	s_waitcnt lgkmcnt(3)
	v_mfma_f32_16x16x32_bf16 v[14:17], v[84:87], v[72:75], v[14:17]
	ds_read_b128 v[84:87], v56 offset:64
	ds_read_b128 v[92:95], v57 offset:64
	ds_read_b128 v[96:99], v58 offset:64
	s_waitcnt lgkmcnt(5)
	v_mfma_f32_16x16x32_bf16 v[2:5], v[88:91], v[72:75], v[2:5]
	s_waitcnt lgkmcnt(3)
	v_mfma_f32_16x16x32_bf16 v[6:9], v[80:83], v[76:79], v[6:9]
	s_waitcnt vmcnt(11)
	ds_write_b128 v0, v[134:137]
	s_waitcnt vmcnt(10)
	ds_write_b128 v0, v[138:141] offset:36864
	s_waitcnt vmcnt(9)
	ds_write_b128 v0, v[142:145] offset:46080
	s_waitcnt lgkmcnt(5)
	v_mfma_f32_16x16x32_bf16 v[10:13], v[84:87], v[76:79], v[10:13]
	s_waitcnt lgkmcnt(4)
	v_mfma_f32_16x16x32_bf16 v[14:17], v[92:95], v[76:79], v[14:17]
	s_waitcnt lgkmcnt(3)
	v_mfma_f32_16x16x32_bf16 v[2:5], v[96:99], v[76:79], v[2:5]
	s_waitcnt lgkmcnt(0)
	s_barrier
	s_add_i32 s4, s26, 4
	s_min_u32 s4, s4, 15
	s_lshl_b32 s4, s4, 7
	v_lshl_add_u64 v[134:135], v[38:39], 0, s[4:5]
	v_lshl_add_u64 v[142:143], v[40:41], 0, s[4:5]
	global_load_dwordx4 v[134:137], v[134:135], off
	global_load_dwordx4 v[138:141], v[142:143], off
	v_add_co_u32_e32 v142, vcc, s34, v142
	s_nop 1
	v_addc_co_u32_e32 v143, vcc, 0, v143, vcc
	global_load_dwordx4 v[142:145], v[142:143], off
	ds_read_b128 v[72:75], v52
	ds_read_b128 v[76:79], v59 offset:36864
	ds_read_b128 v[80:83], v59 offset:39168
	ds_read_b128 v[84:87], v59 offset:41472
	ds_read_b128 v[88:91], v59 offset:43776
	s_waitcnt lgkmcnt(3)
	v_mfma_f32_16x16x32_bf16 v[6:9], v[76:79], v[72:75], v[6:9]
	s_waitcnt lgkmcnt(2)
	v_mfma_f32_16x16x32_bf16 v[10:13], v[80:83], v[72:75], v[10:13]
	ds_read_b128 v[76:79], v52 offset:64
	ds_read_b128 v[80:83], v59 offset:36928
	s_waitcnt lgkmcnt(3)
	v_mfma_f32_16x16x32_bf16 v[14:17], v[84:87], v[72:75], v[14:17]
	ds_read_b128 v[84:87], v59 offset:39232
	ds_read_b128 v[92:95], v59 offset:41536
	ds_read_b128 v[96:99], v59 offset:43840
	s_waitcnt lgkmcnt(5)
	v_mfma_f32_16x16x32_bf16 v[2:5], v[88:91], v[72:75], v[2:5]
	s_waitcnt vmcnt(11)
	ds_write_b128 v0, v[146:149] offset:55296
	s_waitcnt vmcnt(10)
	ds_write_b128 v53, v[150:153]
	s_waitcnt vmcnt(9)
	ds_write_b128 v53, v[154:157] offset:9216
	s_waitcnt lgkmcnt(6)
	v_mfma_f32_16x16x32_bf16 v[18:21], v[80:83], v[76:79], v[6:9]
	s_waitcnt lgkmcnt(5)
	v_mfma_f32_16x16x32_bf16 v[22:25], v[84:87], v[76:79], v[10:13]
	s_waitcnt lgkmcnt(4)
	v_mfma_f32_16x16x32_bf16 v[26:29], v[92:95], v[76:79], v[14:17]
	s_waitcnt lgkmcnt(3)
	v_mfma_f32_16x16x32_bf16 v[2:5], v[96:99], v[76:79], v[2:5]
	s_waitcnt lgkmcnt(0)
	s_barrier
	s_add_i32 s4, s26, 5
	s_min_u32 s4, s4, 15
	s_lshl_b32 s4, s4, 7
	v_lshl_add_u64 v[146:147], v[38:39], 0, s[4:5]
	v_lshl_add_u64 v[154:155], v[40:41], 0, s[4:5]
	global_load_dwordx4 v[146:149], v[146:147], off
	global_load_dwordx4 v[150:153], v[154:155], off
	v_add_co_u32_e32 v154, vcc, s34, v154
	s_nop 1
	v_addc_co_u32_e32 v155, vcc, 0, v155, vcc
	global_load_dwordx4 v[154:157], v[154:155], off
	ds_read_b128 v[72:75], v52 offset:55296
	ds_read_b128 v[76:79], v54
	ds_read_b128 v[80:83], v54 offset:2304
	ds_read_b128 v[84:87], v54 offset:4608
	ds_read_b128 v[88:91], v54 offset:6912
	s_waitcnt lgkmcnt(3)
	v_mfma_f32_16x16x32_bf16 v[18:21], v[76:79], v[72:75], v[18:21]
	s_waitcnt lgkmcnt(2)
	v_mfma_f32_16x16x32_bf16 v[22:25], v[80:83], v[72:75], v[22:25]
	ds_read_b128 v[76:79], v52 offset:55360
	ds_read_b128 v[80:83], v55 offset:64
	ds_read_b128 v[92:95], v56 offset:64
	ds_read_b128 v[96:99], v57 offset:64
	ds_read_b128 v[100:103], v58 offset:64
	s_waitcnt lgkmcnt(5)
	v_mfma_f32_16x16x32_bf16 v[2:5], v[88:91], v[72:75], v[2:5]
	v_mfma_f32_16x16x32_bf16 v[84:87], v[84:87], v[72:75], v[26:29]
	s_waitcnt lgkmcnt(3)
	v_mfma_f32_16x16x32_bf16 v[26:29], v[80:83], v[76:79], v[18:21]
	s_waitcnt vmcnt(11)
	ds_write_b128 v0, v[110:113]
	s_waitcnt vmcnt(10)
	ds_write_b128 v0, v[114:117] offset:36864
	s_waitcnt vmcnt(9)
	ds_write_b128 v0, v[118:121] offset:46080
	s_waitcnt lgkmcnt(5)
	v_mfma_f32_16x16x32_bf16 v[22:25], v[92:95], v[76:79], v[22:25]
	s_waitcnt lgkmcnt(4)
	v_mfma_f32_16x16x32_bf16 v[18:21], v[96:99], v[76:79], v[84:87]
	s_waitcnt lgkmcnt(3)
	v_mfma_f32_16x16x32_bf16 v[2:5], v[100:103], v[76:79], v[2:5]
	s_waitcnt lgkmcnt(0)
	s_barrier
	s_add_i32 s2, s26, 4
	v_lshl_add_u64 v[42:43], v[42:43], 0, s[48:49]
	v_lshl_add_u64 v[44:45], v[44:45], 0, s[48:49]
	s_cmp_gt_u32 s26, 13
	s_mov_b32 s26, s2
	s_cbranch_scc0 .LBB0_1323
	v_add_u32_e32 v0, s17, v48
	s_waitcnt vmcnt(2)
	v_or_b32_e32 v6, v0, v47
	v_cmp_lt_i32_e32 vcc, s97, v6
	v_ashrrev_i32_e32 v0, 11, v0
	v_ashrrev_i32_e32 v7, 31, v6
	s_waitcnt vmcnt(1)
	v_cndmask_b32_e64 v10, v0, 8, vcc
	v_add_u32_e32 v0, 0xffffc000, v6
	v_lshlrev_b64 v[8:9], 12, v[6:7]
	v_lshlrev_b64 v[6:7], 12, v[0:1]
	v_or_b32_e32 v12, s16, v50
	v_lshl_add_u64 v[8:9], s[44:45], 0, v[8:9]
	v_lshl_add_u64 v[6:7], s[12:13], 0, v[6:7]
	v_mul_hi_i32_i24_e32 v11, 0x9000, v10
	v_mul_i32_i24_e32 v10, 0x9000, v10
	v_ashrrev_i32_e32 v13, 31, v12
	v_lshl_add_u64 v[10:11], s[14:15], 0, v[10:11]
	v_cndmask_b32_e32 v7, v9, v7, vcc
	v_cndmask_b32_e32 v6, v8, v6, vcc
	v_lshlrev_b64 v[8:9], 2, v[12:13]
	s_waitcnt vmcnt(0)
	s_waitcnt vmcnt(0)
	v_lshl_add_u64 v[14:15], v[10:11], 0, v[8:9]
	v_lshl_add_u64 v[16:17], v[6:7], 0, v[8:9]
	global_load_dwordx4 v[6:9], v[14:15], off
	global_load_dwordx4 v[10:13], v[16:17], off
	s_waitcnt vmcnt(0)
	v_pk_fma_f32 v[6:7], v[26:27], v[6:7], v[10:11]
	v_pk_fma_f32 v[8:9], v[28:29], v[8:9], v[12:13]
	global_store_dwordx4 v[16:17], v[6:9], off
	global_load_dwordx4 v[6:9], v[14:15], off offset:64
	s_nop 0
	global_load_dwordx4 v[10:13], v[16:17], off offset:64
	s_waitcnt vmcnt(0)
	v_pk_fma_f32 v[6:7], v[22:23], v[6:7], v[10:11]
	v_pk_fma_f32 v[8:9], v[24:25], v[8:9], v[12:13]
	global_store_dwordx4 v[16:17], v[6:9], off offset:64
	global_load_dwordx4 v[6:9], v[14:15], off offset:128
	s_nop 0
	global_load_dwordx4 v[10:13], v[16:17], off offset:128
	s_waitcnt vmcnt(0)
	v_pk_fma_f32 v[6:7], v[18:19], v[6:7], v[10:11]
	v_pk_fma_f32 v[8:9], v[20:21], v[8:9], v[12:13]
	global_store_dwordx4 v[16:17], v[6:9], off offset:128
	global_load_dwordx4 v[6:9], v[14:15], off offset:192
	s_nop 0
	global_load_dwordx4 v[10:13], v[16:17], off offset:192
	s_waitcnt vmcnt(0)
	v_pk_fma_f32 v[2:3], v[2:3], v[6:7], v[10:11]
	v_pk_fma_f32 v[4:5], v[4:5], v[8:9], v[12:13]
	global_store_dwordx4 v[16:17], v[2:5], off offset:192
	s_mov_b32 s31, 0
	s_mov_b32 s26, s23
	s_mov_b32 s4, s25
	s_branch .LBB0_1314

.LBB0_1541:
	s_andn2_b64 vcc, exec, s[16:17]
	s_mov_b32 s25, s50
	s_mov_b32 s4, s31
	s_cbranch_vccnz .LBB0_1534
	s_lshl_b32 s17, s21, 6
	s_addk_i32 s17, 0x4000
	s_lshl_b32 s16, s23, 7
	v_add_u32_e32 v26, s17, v46
	v_mad_i64_i32 v[38:39], s[38:39], v26, s52, v[32:33]
	v_add_u32_e32 v27, s16, v46
	v_mad_i64_i32 v[40:41], s[38:39], v27, s52, v[34:35]
	global_load_dwordx4 v[2:5], v[38:39], off
	global_load_dwordx4 v[18:21], v[40:41], off
	v_add_co_u32_e32 v14, vcc, 0x58000, v40
	v_add_u32_e32 v0, v30, v31
	s_nop 0
	v_addc_co_u32_e32 v15, vcc, 0, v41, vcc
	global_load_dwordx4 v[22:25], v[14:15], off
	global_load_dwordx4 v[122:125], v[38:39], off offset:128
	global_load_dwordx4 v[126:129], v[40:41], off offset:128
	s_nop 0
	global_load_dwordx4 v[130:133], v[14:15], off offset:128
	global_load_dwordx4 v[134:137], v[38:39], off offset:256
	global_load_dwordx4 v[138:141], v[40:41], off offset:256
	global_load_dwordx4 v[142:145], v[14:15], off offset:256
	global_load_dwordx4 v[146:149], v[38:39], off offset:384
	global_load_dwordx4 v[150:153], v[40:41], off offset:384
	global_load_dwordx4 v[154:157], v[14:15], off offset:384
	s_barrier
	s_mov_b32 s25, 2
	s_mov_b32 s3, 0x6035000
	s_waitcnt vmcnt(11)
	ds_write_b128 v0, v[2:5]
	s_waitcnt vmcnt(10)
	ds_write_b128 v0, v[18:21] offset:36864
	s_waitcnt vmcnt(9)
	ds_write_b128 v0, v[22:25] offset:46080
	v_mov_b64_e32 v[2:3], s[46:47]
	v_mad_i64_i32 v[42:43], s[38:39], v27, s52, v[2:3]
	v_mad_i64_i32 v[44:45], s[38:39], v26, s52, v[2:3]
	v_mov_b32_e32 v26, 0
	v_mov_b32_e32 v27, v26
	v_mov_b32_e32 v28, v26
	v_mov_b32_e32 v29, v26
	v_mov_b32_e32 v22, v26
	v_mov_b32_e32 v23, v26
	v_mov_b32_e32 v24, v26
	v_mov_b32_e32 v25, v26
	v_mov_b32_e32 v18, v26
	v_mov_b32_e32 v19, v26
	v_mov_b32_e32 v20, v26
	v_mov_b32_e32 v21, v26
	v_mov_b32_e32 v2, v26
	v_mov_b32_e32 v3, v26
	v_mov_b32_e32 v4, v26
	v_mov_b32_e32 v5, v26
	s_mov_b64 s[38:39], 0x200
	s_waitcnt lgkmcnt(0)
	s_barrier
.LBB0_1543:
	s_add_i32 s4, s25, 2
	s_min_u32 s4, s4, 43
	s_lshl_b32 s4, s4, 7
	v_lshl_add_u64 v[110:111], v[38:39], 0, s[4:5]
	v_lshl_add_u64 v[118:119], v[40:41], 0, s[4:5]
	global_load_dwordx4 v[110:113], v[110:111], off
	global_load_dwordx4 v[114:117], v[118:119], off
	v_add_co_u32_e32 v118, vcc, s92, v118
	s_nop 1
	v_addc_co_u32_e32 v119, vcc, 0, v119, vcc
	global_load_dwordx4 v[118:121], v[118:119], off
	s_mov_b32 s2, 0x1b80000
	s_mov_b32 s2, 0x1bd8000
	s_nop 0
	v_add_u32_e32 v59, v49, v51
	ds_read_b128 v[72:75], v52
	ds_read_b128 v[76:79], v59 offset:36864
	ds_read_b128 v[80:83], v59 offset:39168
	ds_read_b128 v[84:87], v59 offset:41472
	ds_read_b128 v[88:91], v59 offset:43776
	s_waitcnt lgkmcnt(3)
	v_mfma_f32_16x16x32_bf16 v[26:29], v[76:79], v[72:75], v[26:29]
	s_waitcnt lgkmcnt(2)
	v_mfma_f32_16x16x32_bf16 v[22:25], v[80:83], v[72:75], v[22:25]
	ds_read_b128 v[76:79], v52 offset:64
	ds_read_b128 v[80:83], v59 offset:36928
	s_waitcnt lgkmcnt(3)
	v_mfma_f32_16x16x32_bf16 v[18:21], v[84:87], v[72:75], v[18:21]
	ds_read_b128 v[84:87], v59 offset:39232
	ds_read_b128 v[92:95], v59 offset:41536
	ds_read_b128 v[96:99], v59 offset:43840
	s_waitcnt lgkmcnt(5)
	v_mfma_f32_16x16x32_bf16 v[2:5], v[88:91], v[72:75], v[2:5]
	s_waitcnt vmcnt(11)
	ds_write_b128 v0, v[122:125] offset:55296
	s_waitcnt vmcnt(10)
	ds_write_b128 v53, v[126:129]
	s_waitcnt vmcnt(9)
	ds_write_b128 v53, v[130:133] offset:9216
	s_waitcnt lgkmcnt(6)
	v_mfma_f32_16x16x32_bf16 v[6:9], v[80:83], v[76:79], v[26:29]
	s_waitcnt lgkmcnt(5)
	v_mfma_f32_16x16x32_bf16 v[10:13], v[84:87], v[76:79], v[22:25]
	s_waitcnt lgkmcnt(4)
	v_mfma_f32_16x16x32_bf16 v[14:17], v[92:95], v[76:79], v[18:21]
	s_waitcnt lgkmcnt(3)
	v_mfma_f32_16x16x32_bf16 v[2:5], v[96:99], v[76:79], v[2:5]
	s_waitcnt lgkmcnt(0)
	s_barrier
	s_add_i32 s4, s25, 3
	s_min_u32 s4, s4, 43
	s_lshl_b32 s4, s4, 7
	v_lshl_add_u64 v[122:123], v[38:39], 0, s[4:5]
	v_lshl_add_u64 v[130:131], v[40:41], 0, s[4:5]
	global_load_dwordx4 v[122:125], v[122:123], off
	global_load_dwordx4 v[126:129], v[130:131], off
	v_add_co_u32_e32 v130, vcc, s92, v130
	s_nop 1
	v_addc_co_u32_e32 v131, vcc, 0, v131, vcc
	global_load_dwordx4 v[130:133], v[130:131], off
	s_nop 0
	ds_read_b128 v[72:75], v52 offset:55296
	ds_read_b128 v[76:79], v54
	ds_read_b128 v[80:83], v54 offset:2304
	ds_read_b128 v[84:87], v54 offset:4608
	ds_read_b128 v[88:91], v54 offset:6912
	s_waitcnt lgkmcnt(3)
	v_mfma_f32_16x16x32_bf16 v[6:9], v[76:79], v[72:75], v[6:9]
	s_waitcnt lgkmcnt(2)
	v_mfma_f32_16x16x32_bf16 v[10:13], v[80:83], v[72:75], v[10:13]
	ds_read_b128 v[76:79], v52 offset:55360
	ds_read_b128 v[80:83], v55 offset:64
	s_waitcnt lgkmcnt(3)
	v_mfma_f32_16x16x32_bf16 v[14:17], v[84:87], v[72:75], v[14:17]
	ds_read_b128 v[84:87], v56 offset:64
	ds_read_b128 v[92:95], v57 offset:64
	ds_read_b128 v[96:99], v58 offset:64
	s_waitcnt lgkmcnt(5)
	v_mfma_f32_16x16x32_bf16 v[2:5], v[88:91], v[72:75], v[2:5]
	s_waitcnt lgkmcnt(3)
	v_mfma_f32_16x16x32_bf16 v[6:9], v[80:83], v[76:79], v[6:9]
	s_waitcnt vmcnt(11)
	ds_write_b128 v0, v[134:137]
	s_waitcnt vmcnt(10)
	ds_write_b128 v0, v[138:141] offset:36864
	s_waitcnt vmcnt(9)
	ds_write_b128 v0, v[142:145] offset:46080
	s_waitcnt lgkmcnt(5)
	v_mfma_f32_16x16x32_bf16 v[10:13], v[84:87], v[76:79], v[10:13]
	s_waitcnt lgkmcnt(4)
	v_mfma_f32_16x16x32_bf16 v[14:17], v[92:95], v[76:79], v[14:17]
	s_waitcnt lgkmcnt(3)
	v_mfma_f32_16x16x32_bf16 v[2:5], v[96:99], v[76:79], v[2:5]
	s_waitcnt lgkmcnt(0)
	s_barrier
	s_add_i32 s4, s25, 4
	s_min_u32 s4, s4, 43
	s_lshl_b32 s4, s4, 7
	v_lshl_add_u64 v[134:135], v[38:39], 0, s[4:5]
	v_lshl_add_u64 v[142:143], v[40:41], 0, s[4:5]
	global_load_dwordx4 v[134:137], v[134:135], off
	global_load_dwordx4 v[138:141], v[142:143], off
	v_add_co_u32_e32 v142, vcc, s92, v142
	s_nop 1
	v_addc_co_u32_e32 v143, vcc, 0, v143, vcc
	global_load_dwordx4 v[142:145], v[142:143], off
	ds_read_b128 v[72:75], v52
	ds_read_b128 v[76:79], v59 offset:36864
	ds_read_b128 v[80:83], v59 offset:39168
	ds_read_b128 v[84:87], v59 offset:41472
	ds_read_b128 v[88:91], v59 offset:43776
	s_waitcnt lgkmcnt(3)
	v_mfma_f32_16x16x32_bf16 v[6:9], v[76:79], v[72:75], v[6:9]
	s_waitcnt lgkmcnt(2)
	v_mfma_f32_16x16x32_bf16 v[10:13], v[80:83], v[72:75], v[10:13]
	ds_read_b128 v[76:79], v52 offset:64
	ds_read_b128 v[80:83], v59 offset:36928
	s_waitcnt lgkmcnt(3)
	v_mfma_f32_16x16x32_bf16 v[14:17], v[84:87], v[72:75], v[14:17]
	ds_read_b128 v[84:87], v59 offset:39232
	ds_read_b128 v[92:95], v59 offset:41536
	ds_read_b128 v[96:99], v59 offset:43840
	s_waitcnt lgkmcnt(5)
	v_mfma_f32_16x16x32_bf16 v[2:5], v[88:91], v[72:75], v[2:5]
	s_waitcnt vmcnt(11)
	ds_write_b128 v0, v[146:149] offset:55296
	s_waitcnt vmcnt(10)
	ds_write_b128 v53, v[150:153]
	s_waitcnt vmcnt(9)
	ds_write_b128 v53, v[154:157] offset:9216
	s_waitcnt lgkmcnt(6)
	v_mfma_f32_16x16x32_bf16 v[18:21], v[80:83], v[76:79], v[6:9]
	s_waitcnt lgkmcnt(5)
	v_mfma_f32_16x16x32_bf16 v[22:25], v[84:87], v[76:79], v[10:13]
	s_waitcnt lgkmcnt(4)
	v_mfma_f32_16x16x32_bf16 v[26:29], v[92:95], v[76:79], v[14:17]
	s_waitcnt lgkmcnt(3)
	v_mfma_f32_16x16x32_bf16 v[2:5], v[96:99], v[76:79], v[2:5]
	s_waitcnt lgkmcnt(0)
	s_barrier
	s_add_i32 s4, s25, 5
	s_min_u32 s4, s4, 43
	s_lshl_b32 s4, s4, 7
	v_lshl_add_u64 v[146:147], v[38:39], 0, s[4:5]
	v_lshl_add_u64 v[154:155], v[40:41], 0, s[4:5]
	global_load_dwordx4 v[146:149], v[146:147], off
	global_load_dwordx4 v[150:153], v[154:155], off
	v_add_co_u32_e32 v154, vcc, s92, v154
	s_nop 1
	v_addc_co_u32_e32 v155, vcc, 0, v155, vcc
	global_load_dwordx4 v[154:157], v[154:155], off
	ds_read_b128 v[72:75], v52 offset:55296
	ds_read_b128 v[76:79], v54
	ds_read_b128 v[80:83], v54 offset:2304
	ds_read_b128 v[84:87], v54 offset:4608
	ds_read_b128 v[88:91], v54 offset:6912
	s_waitcnt lgkmcnt(3)
	v_mfma_f32_16x16x32_bf16 v[18:21], v[76:79], v[72:75], v[18:21]
	s_waitcnt lgkmcnt(2)
	v_mfma_f32_16x16x32_bf16 v[22:25], v[80:83], v[72:75], v[22:25]
	ds_read_b128 v[76:79], v52 offset:55360
	ds_read_b128 v[80:83], v55 offset:64
	ds_read_b128 v[92:95], v56 offset:64
	ds_read_b128 v[96:99], v57 offset:64
	ds_read_b128 v[100:103], v58 offset:64
	s_waitcnt lgkmcnt(5)
	v_mfma_f32_16x16x32_bf16 v[2:5], v[88:91], v[72:75], v[2:5]
	v_mfma_f32_16x16x32_bf16 v[84:87], v[84:87], v[72:75], v[26:29]
	s_waitcnt lgkmcnt(3)
	v_mfma_f32_16x16x32_bf16 v[26:29], v[80:83], v[76:79], v[18:21]
	s_waitcnt vmcnt(11)
	ds_write_b128 v0, v[110:113]
	s_waitcnt vmcnt(10)
	ds_write_b128 v0, v[114:117] offset:36864
	s_waitcnt vmcnt(9)
	ds_write_b128 v0, v[118:121] offset:46080
	s_waitcnt lgkmcnt(5)
	v_mfma_f32_16x16x32_bf16 v[22:25], v[92:95], v[76:79], v[22:25]
	s_waitcnt lgkmcnt(4)
	v_mfma_f32_16x16x32_bf16 v[18:21], v[96:99], v[76:79], v[84:87]
	s_waitcnt lgkmcnt(3)
	v_mfma_f32_16x16x32_bf16 v[2:5], v[100:103], v[76:79], v[2:5]
	s_waitcnt lgkmcnt(0)
	s_barrier
	s_add_i32 s2, s25, 4
	v_lshl_add_u64 v[42:43], v[42:43], 0, s[38:39]
	v_lshl_add_u64 v[44:45], v[44:45], 0, s[38:39]
	s_cmp_gt_u32 s25, 41
	s_mov_b32 s25, s2
	s_cbranch_scc0 .LBB0_1543
	v_add_u32_e32 v0, s17, v48
	s_waitcnt vmcnt(2)
	v_or_b32_e32 v6, v0, v47
	v_cmp_lt_i32_e32 vcc, s97, v6
	v_ashrrev_i32_e32 v0, 11, v0
	v_ashrrev_i32_e32 v7, 31, v6
	s_waitcnt vmcnt(1)
	v_cndmask_b32_e64 v10, v0, 8, vcc
	v_add_u32_e32 v0, 0xffffc000, v6
	v_or_b32_e32 v12, s16, v50
	v_lshlrev_b64 v[8:9], 12, v[6:7]
	v_lshlrev_b64 v[6:7], 12, v[0:1]
	v_mul_hi_i32_i24_e32 v11, 0x9000, v10
	v_mul_i32_i24_e32 v10, 0x9000, v10
	v_ashrrev_i32_e32 v13, 31, v12
	v_lshl_add_u64 v[8:9], s[44:45], 0, v[8:9]
	v_lshl_add_u64 v[6:7], s[12:13], 0, v[6:7]
	v_lshl_add_u64 v[10:11], s[14:15], 0, v[10:11]
	v_lshlrev_b64 v[12:13], 2, v[12:13]
	s_waitcnt vmcnt(0)
	s_waitcnt vmcnt(0)
	v_cndmask_b32_e32 v15, v9, v7, vcc
	v_cndmask_b32_e32 v14, v8, v6, vcc
	v_lshl_add_u64 v[16:17], v[10:11], 0, v[12:13]
	global_load_dwordx4 v[6:9], v[16:17], off
	v_lshl_add_u64 v[14:15], v[14:15], 0, v[12:13]
	global_load_dwordx4 v[10:13], v[14:15], off
	s_waitcnt vmcnt(1)
	v_pk_mul_f32 v[6:7], v[6:7], 0.5 op_sel_hi:[1,0]
	v_pk_mul_f32 v[8:9], v[8:9], 0.5 op_sel_hi:[1,0]
	s_waitcnt vmcnt(0)
	v_pk_fma_f32 v[6:7], v[26:27], v[6:7], v[10:11]
	v_pk_fma_f32 v[8:9], v[28:29], v[8:9], v[12:13]
	global_store_dwordx4 v[14:15], v[6:9], off
	global_load_dwordx4 v[6:9], v[16:17], off offset:64
	s_nop 0
	global_load_dwordx4 v[10:13], v[14:15], off offset:64
	s_waitcnt vmcnt(1)
	v_pk_mul_f32 v[6:7], v[6:7], 0.5 op_sel_hi:[1,0]
	v_pk_mul_f32 v[8:9], v[8:9], 0.5 op_sel_hi:[1,0]
	s_waitcnt vmcnt(0)
	v_pk_fma_f32 v[6:7], v[22:23], v[6:7], v[10:11]
	v_pk_fma_f32 v[8:9], v[24:25], v[8:9], v[12:13]
	global_store_dwordx4 v[14:15], v[6:9], off offset:64
	global_load_dwordx4 v[6:9], v[16:17], off offset:128
	s_nop 0
	global_load_dwordx4 v[10:13], v[14:15], off offset:128
	s_waitcnt vmcnt(1)
	v_pk_mul_f32 v[6:7], v[6:7], 0.5 op_sel_hi:[1,0]
	v_pk_mul_f32 v[8:9], v[8:9], 0.5 op_sel_hi:[1,0]
	s_waitcnt vmcnt(0)
	v_pk_fma_f32 v[6:7], v[18:19], v[6:7], v[10:11]
	v_pk_fma_f32 v[8:9], v[20:21], v[8:9], v[12:13]
	global_store_dwordx4 v[14:15], v[6:9], off offset:128
	global_load_dwordx4 v[6:9], v[16:17], off offset:192
	s_nop 0
	global_load_dwordx4 v[10:13], v[14:15], off offset:192
	s_waitcnt vmcnt(1)
	v_pk_mul_f32 v[6:7], v[6:7], 0.5 op_sel_hi:[1,0]
	v_pk_mul_f32 v[8:9], v[8:9], 0.5 op_sel_hi:[1,0]
	s_waitcnt vmcnt(0)
	v_pk_fma_f32 v[2:3], v[2:3], v[6:7], v[10:11]
	v_pk_fma_f32 v[4:5], v[4:5], v[8:9], v[12:13]
	global_store_dwordx4 v[14:15], v[2:5], off offset:192
	s_mov_b32 s26, 0
	s_mov_b32 s25, s21
	s_mov_b32 s4, s23
	s_mov_b64 s[38:39], 0x1000
	s_branch .LBB0_1534
